# windowed attention: V fragments prefetched before softmax, cross-half max via permlane32_swap instead of ds_bpermute
# baseline (speedup 1.0000x reference)
; #define LAS __attribute__((address_space(3)))
; __device__ __forceinline__ void attn_win(LAS unsigned char* lds, const bf16_t* __restrict__ PROJ, const bf16_t* __restrict__ VT, bf16_t* __restrict__ AO, ...
;     ...
;         if ((k0 + 63 >= qw - 128) && (k0 <= qw + 31 + 128)) {
;             const LAS unsigned char* kb = lds + OFF_K + cur * TB + r32 * KP + hi * 16;
;             f32x16 sA = {}, sB = {};
; #pragma unroll
;             for (int ds = 0; ds < 4; ++ds) {
;                 const bf16x8 ka = *(const LAS bf16x8*)(kb + ds * 32);
;                 const bf16x8 kb2 = *(const LAS bf16x8*)(kb + 32 * KP + ds * 32);
;                 sA = __builtin_amdgcn_mfma_f32_32x32x16_bf16(ka, qf[ds], sA, 0, 0, 0);
;                 sB = __builtin_amdgcn_mfma_f32_32x32x16_bf16(kb2, qf[ds], sB, 0, 0, 0);
;             }
;             { const LAS float* lp = lut + (k0 - (qw + r32) + 224 + 4 * hi);
; #pragma unroll
;               for (int r = 0; r < 16; ++r) { sA[r] += lp[(r & 3) + 8 * (r >> 2)]; sB[r] += lp[32 + (r & 3) + 8 * (r >> 2)]; } }
.LBB0_268:
	s_add_i32 s30, s10, 63
	s_cmp_lt_i32 s30, s11
	s_cselect_b64 s[30:31], -1, 0
	s_cmp_gt_u32 s10, s12
	s_cselect_b64 s[64:65], -1, 0
	s_or_b64 s[30:31], s[30:31], s[64:65]
	s_and_b64 vcc, exec, s[30:31]
	s_cbranch_vccnz .LBB0_264
	s_mulk_i32 s14, 0x2400
	v_add_u32_e32 v97, s14, v95
	ds_read_b128 v[48:51], v97 offset:4608
	s_waitcnt lgkmcnt(3)
	ds_read_b128 v[32:35], v97
	ds_read_b128 v[100:103], v97 offset:32
	ds_read_b128 v[104:107], v97 offset:4640
	s_waitcnt lgkmcnt(3)
	v_mfma_f32_32x32x16_bf16 v[48:63], v[48:51], v[64:67], 0
	s_waitcnt lgkmcnt(2)
	v_mfma_f32_32x32x16_bf16 v[32:47], v[32:35], v[64:67], 0
	s_waitcnt lgkmcnt(1)
	v_mfma_f32_32x32x16_bf16 v[32:47], v[100:103], v[68:71], v[32:47]
	s_waitcnt lgkmcnt(0)
	v_mfma_f32_32x32x16_bf16 v[48:63], v[104:107], v[68:71], v[48:63]
	ds_read_b128 v[100:103], v97 offset:64
	ds_read_b128 v[104:107], v97 offset:4672
	s_waitcnt vmcnt(1) lgkmcnt(1)
	v_mfma_f32_32x32x16_bf16 v[32:47], v[100:103], v[72:75], v[32:47]
	s_waitcnt lgkmcnt(0)
	v_mfma_f32_32x32x16_bf16 v[48:63], v[104:107], v[72:75], v[48:63]
	ds_read_b128 v[100:103], v97 offset:96
	ds_read_b128 v[104:107], v97 offset:4704
	s_waitcnt vmcnt(0) lgkmcnt(1)
	v_mfma_f32_32x32x16_bf16 v[32:47], v[100:103], v[80:83], v[32:47]
	ds_read2_b32 v[206:207], v96 offset1:1
	ds_read2_b32 v[208:209], v96 offset0:32 offset1:33
	ds_read2_b32 v[210:211], v96 offset0:2 offset1:3
	ds_read2_b32 v[212:213], v96 offset0:34 offset1:35
	ds_read2_b32 v[214:215], v96 offset0:8 offset1:9
	ds_read2_b32 v[216:217], v96 offset0:40 offset1:41
	ds_read2_b32 v[218:219], v96 offset0:10 offset1:11
	ds_read2_b32 v[220:221], v96 offset0:42 offset1:43
	ds_read2_b32 v[222:223], v96 offset0:16 offset1:17
	ds_read2_b32 v[224:225], v96 offset0:48 offset1:49
	ds_read2_b32 v[226:227], v96 offset0:18 offset1:19
	ds_read2_b32 v[228:229], v96 offset0:50 offset1:51
	ds_read2_b32 v[230:231], v96 offset0:24 offset1:25
	ds_read2_b32 v[232:233], v96 offset0:56 offset1:57
	s_waitcnt lgkmcnt(14)
	v_mfma_f32_32x32x16_bf16 v[48:63], v[104:107], v[80:83], v[48:63]
	ds_read2_b32 v[234:235], v96 offset0:26 offset1:27
	ds_read2_b32 v[236:237], v96 offset0:58 offset1:59
	s_waitcnt lgkmcnt(0)
; __device__ __forceinline__ void attn_win(LAS unsigned char* lds, const bf16_t* __restrict__ PROJ, const bf16_t* __restrict__ VT, bf16_t* __restrict__ AO, ...
;     ...
;             float mx0 = fmaxf(sA[0], sB[0]), mx1 = fmaxf(sA[1], sB[1]), mx2 = fmaxf(sA[2], sB[2]), mx3 = fmaxf(sA[3], sB[3]);
; #pragma unroll
;             for (int r = 4; r < 16; r += 4) { mx0 = fmaxf(mx0, fmaxf(sA[r], sB[r])); mx1 = fmaxf(mx1, fmaxf(sA[r + 1], sB[r + 1])); mx2 = fmaxf(mx2, fmaxf(sA[r + 2], sB[r + 2])); mx3 = fmaxf(mx3, fmaxf(sA[r + 3], sB[r + 3])); }
;             float mx = fmaxf(fmaxf(mx0, mx1), fmaxf(mx2, mx3));
;             mx = fmaxf(mx, __shfl_xor(mx, 32));
;             const float mn = fmaxf(m, mx);
;             const float alpha = __builtin_amdgcn_exp2f(m - mn);
;             m = mn;
;             float ps0 = 0.f, ps1 = 0.f, ps2 = 0.f, ps3 = 0.f;
; #pragma unroll
;             for (int r = 0; r < 16; r += 4) {
; #pragma unroll
;                 for (int q = 0; q < 4; ++q) { sA[r + q] = __builtin_amdgcn_exp2f(sA[r + q] - mn); sB[r + q] = __builtin_amdgcn_exp2f(sB[r + q] - mn); }
;                 ps0 += sA[r] + sB[r]; ps1 += sA[r + 1] + sB[r + 1]; ps2 += sA[r + 2] + sB[r + 2]; ps3 += sA[r + 3] + sB[r + 3]; }
;             l = l * alpha + ((ps0 + ps1) + (ps2 + ps3));
; #pragma unroll
;             for (int r = 0; r < 16; ++r) { o0[r] *= alpha; o1[r] *= alpha; }
;             bf16x8 pk[4];
;             { u32x4 w;
;               w.x = cvtpk(sA[0], sA[1]); w.y = cvtpk(sA[2], sA[3]); w.z = cvtpk(sA[4], sA[5]); w.w = cvtpk(sA[6], sA[7]); pk[0] = __builtin_bit_cast(bf16x8, w);
;               w.x = cvtpk(sA[8], sA[9]); w.y = cvtpk(sA[10], sA[11]); w.z = cvtpk(sA[12], sA[13]); w.w = cvtpk(sA[14], sA[15]); pk[1] = __builtin_bit_cast(bf16x8, w);
;               w.x = cvtpk(sB[0], sB[1]); w.y = cvtpk(sB[2], sB[3]); w.z = cvtpk(sB[4], sB[5]); w.w = cvtpk(sB[6], sB[7]); pk[2] = __builtin_bit_cast(bf16x8, w);
;               w.x = cvtpk(sB[8], sB[9]); w.y = cvtpk(sB[10], sB[11]); w.z = cvtpk(sB[12], sB[13]); w.w = cvtpk(sB[14], sB[15]); pk[3] = __builtin_bit_cast(bf16x8, w); }
;             const LAS unsigned char* vb = lds + OFF_V + cur * TB + r32 * KP + hi * 16;
; #pragma unroll
;             for (int s = 0; s < 4; ++s) {
;                 const bf16x8 va = *(const LAS bf16x8*)(vb + s * 32);
;                 const bf16x8 vb2 = *(const LAS bf16x8*)(vb + 32 * KP + s * 32);
	s_nop 6
	v_add_f32_e32 v99, v32, v206
	v_add_f32_e32 v101, v33, v207
	v_add_f32_e32 v100, v48, v208
	v_add_f32_e32 v102, v49, v209
	v_add_f32_e32 v103, v34, v210
	v_add_f32_e32 v48, v50, v212
	v_add_f32_e32 v50, v35, v211
	v_add_f32_e32 v49, v51, v213
	v_add_f32_e32 v51, v36, v214
	v_add_f32_e32 v52, v52, v216
	v_add_f32_e32 v104, v37, v215
	v_add_f32_e32 v53, v53, v217
	v_add_f32_e32 v105, v38, v218
	v_add_f32_e32 v54, v54, v220
	v_add_f32_e32 v106, v39, v219
	v_add_f32_e32 v55, v55, v221
	v_max_f32_e32 v36, v106, v55
	v_max3_f32 v36, v50, v49, v36
	v_add_f32_e32 v107, v40, v222
	v_add_f32_e32 v108, v56, v224
	v_add_f32_e32 v109, v41, v223
	v_add_f32_e32 v57, v57, v225
	v_max_f32_e32 v37, v107, v108
	v_max_f32_e32 v38, v109, v57
	v_add_f32_e32 v110, v42, v226
	v_add_f32_e32 v111, v58, v228
	v_add_f32_e32 v112, v43, v227
	v_add_f32_e32 v113, v59, v229
	v_max_f32_e32 v39, v110, v111
	v_add_f32_e32 v44, v44, v230
	v_add_f32_e32 v114, v60, v232
	v_add_f32_e32 v115, v45, v231
	v_add_f32_e32 v116, v61, v233
	v_add_f32_e32 v117, v46, v234
	v_add_f32_e32 v119, v47, v235
	v_add_f32_e32 v120, v63, v237
	v_max_f32_e32 v32, v103, v48
	v_max_f32_e32 v33, v51, v52
	v_max_f32_e32 v35, v105, v54
	v_add_f32_e32 v118, v62, v236
	v_max3_f32 v33, v99, v100, v33
	v_max_f32_e32 v34, v104, v53
	v_max3_f32 v32, v32, v35, v39
	v_max_f32_e32 v39, v44, v114
	v_max3_f32 v34, v101, v102, v34
	v_max3_f32 v33, v33, v37, v39
	v_max_f32_e32 v37, v115, v116
	v_max_f32_e32 v35, v112, v113
	v_max3_f32 v34, v34, v38, v37
	v_max_f32_e32 v38, v119, v120
	v_max_f32_e32 v37, v117, v118
	v_max3_f32 v35, v36, v35, v38
	v_max3_f32 v32, v32, v37, v35
	v_max3_f32 v32, v33, v34, v32
	ds_read_b128 v[206:209], v97 offset:18432
	ds_read_b128 v[210:213], v97 offset:23040
	ds_read_b128 v[214:217], v97 offset:18464
	ds_read_b128 v[218:221], v97 offset:23072
	ds_read_b128 v[222:225], v97 offset:18496
	ds_read_b128 v[226:229], v97 offset:23104
	ds_read_b128 v[230:233], v97 offset:18528
	ds_read_b128 v[234:237], v97 offset:23136
	v_mov_b32_e32 v33, v32
	s_nop 1
	v_permlane32_swap_b32_e32 v32, v33
	v_max3_f32 v45, v98, v32, v33
	v_sub_f32_e32 v33, v101, v45
	v_sub_f32_e32 v35, v50, v45
	v_sub_f32_e32 v50, v107, v45
	v_exp_f32_e32 v38, v33
	v_sub_f32_e32 v33, v102, v45
	v_sub_f32_e32 v41, v52, v45
	v_exp_f32_e32 v56, v50
	v_sub_f32_e32 v50, v108, v45
	v_sub_f32_e32 v32, v99, v45
	v_exp_f32_e32 v34, v33
	v_sub_f32_e32 v33, v103, v45
	v_exp_f32_e32 v46, v41
	v_sub_f32_e32 v41, v104, v45
	v_exp_f32_e32 v58, v50
	v_sub_f32_e32 v50, v109, v45
	v_sub_f32_e32 v44, v44, v45
	v_sub_f32_e32 v121, v98, v45
	v_exp_f32_e32 v36, v32
	v_sub_f32_e32 v32, v100, v45
	v_exp_f32_e32 v37, v33
	v_sub_f32_e32 v33, v48, v45
	v_exp_f32_e32 v42, v41
	v_sub_f32_e32 v41, v53, v45
	v_exp_f32_e32 v60, v50
	v_sub_f32_e32 v50, v57, v45
	v_exp_f32_e32 v98, v44
	v_sub_f32_e32 v44, v114, v45
	v_exp_f32_e32 v32, v32
	v_exp_f32_e32 v33, v33
	v_exp_f32_e32 v39, v35
	v_sub_f32_e32 v35, v49, v45
	v_sub_f32_e32 v40, v51, v45
	v_exp_f32_e32 v48, v41
	v_sub_f32_e32 v41, v105, v45
	v_sub_f32_e32 v43, v54, v45
	v_exp_f32_e32 v62, v50
	v_sub_f32_e32 v50, v110, v45
	v_exp_f32_e32 v100, v44
	v_sub_f32_e32 v44, v115, v45
	v_exp_f32_e32 v35, v35
	v_exp_f32_e32 v40, v40
	v_exp_f32_e32 v41, v41
	v_exp_f32_e32 v47, v43
	v_sub_f32_e32 v43, v106, v45
	v_sub_f32_e32 v49, v55, v45
	v_exp_f32_e32 v57, v50
	v_sub_f32_e32 v50, v111, v45
	v_exp_f32_e32 v102, v44
	v_sub_f32_e32 v44, v116, v45
	v_exp_f32_e32 v43, v43
	v_exp_f32_e32 v49, v49
	v_exp_f32_e32 v59, v50
	v_sub_f32_e32 v50, v112, v45
	v_exp_f32_e32 v104, v44
	v_sub_f32_e32 v44, v117, v45
	v_exp_f32_e32 v61, v50
	v_sub_f32_e32 v50, v113, v45
	v_exp_f32_e32 v99, v44
	v_sub_f32_e32 v44, v118, v45
	v_exp_f32_e32 v63, v50
	v_exp_f32_e32 v101, v44
	v_sub_f32_e32 v44, v119, v45
	v_add_f32_e32 v50, v32, v36
	v_add_f32_e32 v51, v33, v37
	v_exp_f32_e32 v103, v44
	v_sub_f32_e32 v44, v120, v45
	v_add_f32_e32 v52, v34, v38
	v_add_f32_e32 v53, v35, v39
	v_add_f32_e32 v54, v46, v40
	v_add_f32_e32 v55, v47, v41
	v_exp_f32_e32 v105, v44
	v_add_f32_e32 v50, v54, v50
	v_add_f32_e32 v51, v55, v51
	v_add_f32_e32 v54, v48, v42
	v_add_f32_e32 v55, v49, v43
	v_exp_f32_e32 v44, v121
	v_add_f32_e32 v52, v54, v52
	v_add_f32_e32 v53, v55, v53
	v_add_f32_e32 v54, v58, v56
	v_add_f32_e32 v55, v59, v57
	v_mul_f32_e32 v14, v14, v44
	v_mul_f32_e32 v15, v15, v44
	v_add_f32_e32 v50, v54, v50
	v_add_f32_e32 v51, v55, v51
	v_add_f32_e32 v54, v62, v60
	v_add_f32_e32 v55, v63, v61
	v_mul_f32_e32 v12, v12, v44
	v_mul_f32_e32 v13, v13, v44
	v_add_f32_e32 v52, v54, v52
	v_add_f32_e32 v53, v55, v53
	v_add_f32_e32 v54, v100, v98
	v_add_f32_e32 v55, v101, v99
	v_mul_f32_e32 v10, v10, v44
	v_mul_f32_e32 v11, v11, v44
	v_add_f32_e32 v50, v54, v50
	v_add_f32_e32 v51, v55, v51
	v_add_f32_e32 v54, v104, v102
	v_add_f32_e32 v55, v105, v103
	v_mul_f32_e32 v8, v8, v44
	v_mul_f32_e32 v9, v9, v44
	v_add_f32_e32 v52, v54, v52
	v_add_f32_e32 v53, v55, v53
	v_cvt_pk_bf16_f32 v54, v40, v42
	v_add_f32_e32 v50, v50, v52
	v_add_f32_e32 v51, v51, v53
	v_cvt_pk_bf16_f32 v52, v36, v38
	v_cvt_pk_bf16_f32 v53, v37, v39
	v_cvt_pk_bf16_f32 v55, v41, v43
	v_cvt_pk_bf16_f32 v40, v56, v60
	v_cvt_pk_bf16_f32 v41, v57, v61
	v_cvt_pk_bf16_f32 v36, v32, v34
	v_cvt_pk_bf16_f32 v37, v33, v35
	v_cvt_pk_bf16_f32 v38, v46, v48
	v_cvt_pk_bf16_f32 v39, v47, v49
	v_cvt_pk_bf16_f32 v32, v58, v62
	v_cvt_pk_bf16_f32 v33, v59, v63
	v_mul_f32_e32 v6, v6, v44
	v_mul_f32_e32 v7, v7, v44
	v_mul_f32_e32 v4, v4, v44
	v_mul_f32_e32 v5, v5, v44
	v_mul_f32_e32 v2, v2, v44
	v_mul_f32_e32 v3, v3, v44
	v_mul_f32_e32 v0, v0, v44
	v_mul_f32_e32 v1, v1, v44
	v_mul_f32_e32 v30, v30, v44
	v_mul_f32_e32 v31, v31, v44
	v_mul_f32_e32 v28, v28, v44
	v_mul_f32_e32 v29, v29, v44
	v_mul_f32_e32 v26, v26, v44
	v_mul_f32_e32 v27, v27, v44
	v_mul_f32_e32 v24, v24, v44
	v_mul_f32_e32 v25, v25, v44
	v_mul_f32_e32 v22, v22, v44
	v_mul_f32_e32 v23, v23, v44
	v_mul_f32_e32 v20, v20, v44
	v_mul_f32_e32 v21, v21, v44
	v_mul_f32_e32 v18, v18, v44
	v_mul_f32_e32 v19, v19, v44
	v_mul_f32_e32 v16, v16, v44
	v_mul_f32_e32 v17, v17, v44
	s_waitcnt lgkmcnt(0)
	v_mfma_f32_32x32x16_bf16 v[0:15], v[206:209], v[52:55], v[0:15]
	v_cvt_pk_bf16_f32 v42, v98, v102
	v_cvt_pk_bf16_f32 v43, v99, v103
	v_cvt_pk_bf16_f32 v34, v100, v104
	v_cvt_pk_bf16_f32 v35, v101, v105
	v_add_f32_e32 v50, v50, v51
	v_fmac_f32_e32 v50, v94, v44
	v_mov_b32_e32 v94, v50
	v_mfma_f32_32x32x16_bf16 v[16:31], v[210:213], v[52:55], v[16:31]
	v_mov_b32_e32 v98, v45
	v_mfma_f32_32x32x16_bf16 v[0:15], v[214:217], v[40:43], v[0:15]
	v_mfma_f32_32x32x16_bf16 v[16:31], v[218:221], v[40:43], v[16:31]
	v_mfma_f32_32x32x16_bf16 v[0:15], v[222:225], v[36:39], v[0:15]
	v_mfma_f32_32x32x16_bf16 v[16:31], v[226:229], v[36:39], v[16:31]
	v_mfma_f32_32x32x16_bf16 v[0:15], v[230:233], v[32:35], v[0:15]
	v_mfma_f32_32x32x16_bf16 v[16:31], v[234:237], v[32:35], v[16:31]
	s_branch .LBB0_264
